# P2: shift_mu slices of the workgroup's two heads copied once into spare LDS; the nine per-item shift_mu global loads become ds_read_b128 (item-top global burst 15 -> 6 loads)
# speedup vs baseline: 1.0072x; 1.0072x over previous
; __device__ void rwkv_prep_item(const Params& p, char* lds_, int item, PrepRaw& raw, int next_item) {
;     ...
;   const int tid = threadIdx.x, lane = tid & 63, wave = tid >> 6;
;   const int b = item >> 9, hd = (item >> 6) & 7, c = item & 63;
;   constexpr int RB = 64 * LD * 2;
;   u16* At = (u16*)(lds + 0 * RB);  u16* Bt = (u16*)(lds + 1 * RB);  u16* Kt = (u16*)(lds + 2 * RB);  u16* Rt = (u16*)(lds + 3 * RB);
;   u16* AT = (u16*)(lds + 4 * RB);  u16* BT = (u16*)(lds + 5 * RB);  u16* KT = (u16*)(lds + 6 * RB);  u16* VT = (u16*)(lds + 7 * RB);
;   u16* LAK = (u16*)(lds + 8 * RB); u16* MRB = (u16*)(lds + 9 * RB); u16* MRK = (u16*)(lds + 10 * RB); u16* TB = (u16*)(lds + 11 * RB);
;   float* Tf = (float*)(lds + 12 * RB);
;   float* gC = (float*)(lds + 12 * RB + 64 * 68 * 4);
;   float* Za = (float*)(lds + 12 * RB + 64 * 68 * 4 + 256);
;   u16* X1T = At; u16* WT = Bt; u16* U0T = Kt;
;   u16* TW = LAK; u16* AD = MRB; u16* DUs = MRK; u16* IUs = TB;
;   float* Zw = Tf; float* G = Tf;
;   const int t = tid >> 3, cg8 = (tid & 7) * 8;
;   const int pos = c * 64 + t;
;   const size_t tokrow = (size_t)b * SEQ + pos;
;   const u16* prow = p.PB + tokrow * PBW;
;   const bool hasprev = pos > 0;
;   float rr[8], kk_[8], vv[8];
;   f32x4 pdb[2], pib[2], pkk[2], pka[2], prk[2];
;     ...
;       const int j0 = (jt0 + jj) * 16 + 4 * mg;
;       f32x4 o; float x1[4], x2[4], x3[4];
; #pragma unroll
;       for (int e = 0; e < 4; ++e) {
;         const int j = j0 + e;
;         o[e] = (j < mi) ? lab[jj][e] : 0.f;
;         x1[e] = (j < mi) ? lak[jj][e] : 0.f;
;         x2[e] = (j <= mi) ? mrb[jj][e] : 0.f;
;         x3[e] = (j <= mi) ? mrk[jj][e] : 0.f;
;       }
.LBB0_273:
.LBB0_274:
	v_bfe_u32 v115, v223, 4, 2
	s_andn2_b64 vcc, exec, s[4:5]
	v_lshrrev_b32_e32 v158, 6, v223
	v_and_b32_e32 v174, 15, v223
	v_lshrrev_b32_e32 v175, 1, v223
	v_lshlrev_b32_e32 v114, 2, v115
	s_cbranch_vccnz .LBB0_330
	v_lshlrev_b32_e32 v28, 5, v158
	v_and_or_b32 v30, v28, 32, v174
	v_and_b32_e32 v29, 24, v175
	v_mul_u32_u24_e32 v24, 0x48, v30
	s_add_i32 s5, 0, 0x18d00
	v_and_b32_e32 v26, 0x70, v240
	v_lshlrev_b32_e32 v35, 1, v24
	v_or_b32_e32 v36, 32, v29
	v_or_b32_e32 v27, v26, v174
	v_lshlrev_b32_e32 v31, 1, v29
	v_lshlrev_b32_e32 v37, 1, v36
	v_add_u32_e32 v24, s5, v35
	v_add_u32_e32 v167, v24, v31
	v_add_u32_e32 v168, v24, v37
	v_mul_u32_u24_e32 v24, 0x44, v27
	v_bfe_u32 v25, v223, 6, 1
	v_lshlrev_b32_e32 v24, 2, v24
	s_add_i32 s15, 0, 0x1b100
	s_add_i32 s74, 0, 0x1f600
	v_add_u32_e32 v39, s15, v24
	v_add_u32_e32 v40, s74, v24
	v_lshlrev_b32_e32 v41, 7, v25
	v_and_b32_e32 v24, 48, v223
	v_and_b32_e32 v116, 56, v219
	v_add3_u32 v170, v39, v24, v41
	v_mul_u32_u24_e32 v39, 0x44, v240
	v_add_lshl_u32 v39, v39, v116, 2
	v_add_u32_e32 v172, s15, v39
	v_add_u32_e32 v173, s74, v39
	v_add_u32_e32 v39, 16, v39
	v_add_u32_e32 v176, s15, v39
	v_add_u32_e32 v177, s74, v39
	v_mbcnt_hi_u32_b32 v39, -1, v241
	v_add3_u32 v171, v40, v24, v41
	v_and_b32_e32 v41, 64, v39
	v_xor_b32_e32 v40, 1, v39
	v_add_u32_e32 v41, 64, v41
	v_cmp_lt_i32_e32 vcc, v40, v41
	v_mul_u32_u24_e32 v22, 0x48, v240
	v_mov_b32_e32 v242, v241
	v_cndmask_b32_e32 v40, v39, v40, vcc
	v_lshlrev_b32_e32 v178, 2, v40
	v_xor_b32_e32 v40, 2, v39
	v_cmp_lt_i32_e32 vcc, v40, v41
	s_add_i32 s14, 0, 0x12100
	v_lshlrev_b32_e32 v23, 1, v22
	v_cndmask_b32_e32 v40, v39, v40, vcc
	v_lshlrev_b32_e32 v179, 2, v40
	v_xor_b32_e32 v40, 4, v39
	v_cmp_lt_i32_e32 vcc, v40, v41
	v_lshlrev_b32_e32 v22, 1, v116
	s_add_i32 s4, 0, 0x14500
	v_cndmask_b32_e32 v39, v39, v40, vcc
	v_cmp_eq_u32_e32 vcc, 0, v174
	s_add_i32 s10, 0, 0x16900
	v_mul_u32_u24_e32 v47, 0x110, v24
	v_cndmask_b32_e64 v190, 0, 1.0, vcc
	v_cmp_eq_u32_e32 vcc, 1, v174
	v_lshlrev_b32_e32 v48, 2, v24
	v_add3_u32 v117, s14, v23, v22
	v_cndmask_b32_e64 v191, 0, 1.0, vcc
	v_cmp_eq_u32_e32 vcc, 2, v174
	v_cndmask_b32_e64 v253, 0, 1.0, vcc
	v_cmp_eq_u32_e32 vcc, 3, v174
	v_mul_u32_u24_e32 v32, 0x48, v27
	v_cndmask_b32_e64 v254, 0, 1.0, vcc
	v_cmp_eq_u32_e32 vcc, 4, v174
	v_add3_u32 v184, 0, v23, v22
	v_bitop3_b32 v23, v219, v240, 56 bitop3:0x6c
	v_cndmask_b32_e64 v255, 0, 1.0, vcc
	v_cmp_eq_u32_e32 vcc, 5, v174
	v_add3_u32 v189, s15, v47, v48
	v_lshlrev_b32_e32 v47, 2, v174
	v_cndmask_b32_e64 v241, 0, 1.0, vcc
	v_cmp_eq_u32_e32 vcc, 6, v174
	v_or_b32_e32 v48, 16, v28
	v_lshlrev_b32_e32 v120, 6, v25
	v_cndmask_b32_e64 v196, 0, 1.0, vcc
	v_cmp_eq_u32_e32 vcc, 7, v174
	v_lshlrev_b32_e32 v32, 1, v32
	s_movk_i32 s16, 0x110
	v_cndmask_b32_e64 v197, 0, 1.0, vcc
	v_cmp_eq_u32_e32 vcc, 8, v174
	v_mul_u32_u24_e32 v43, 0x90, v116
	v_lshlrev_b32_e32 v23, 1, v23
	v_cndmask_b32_e64 v198, 0, 1.0, vcc
	v_cmp_eq_u32_e32 vcc, 9, v174
	v_or_b32_e32 v49, v48, v174
	v_add3_u32 v211, s15, v120, v47
	v_or_b32_e32 v26, v114, v26
	v_add3_u32 v185, 0, v43, v23
	v_add_u32_e32 v23, 0, v32
	v_cndmask_b32_e64 v199, 0, 1.0, vcc
	v_cmp_eq_u32_e32 vcc, 10, v174
	v_mul_u32_u24_e32 v49, 0x110, v49
	v_lshl_add_u32 v50, v158, 7, s15
	v_or_b32_e32 v28, v28, v115
	v_mul_u32_u24_e32 v52, 0x84, v26
	v_mad_u32_u24 v212, v26, s16, v211
	v_bitop3_b32 v26, v27, v29, 56 bitop3:0x6c
	v_cndmask_b32_e64 v200, 0, 1.0, vcc
	v_cmp_eq_u32_e32 vcc, 11, v174
	v_add3_u32 v207, v50, v49, v114
	v_add_u32_e32 v49, v50, v47
	v_mul_u32_u24_e32 v50, 0x110, v28
	v_mul_u32_u24_e32 v28, 0x440, v158
	v_lshl_add_u32 v213, v26, 1, v23
	v_add_u32_e32 v26, s14, v35
	v_lshlrev_b32_e32 v180, 2, v39
	v_mul_u32_u24_e32 v39, 0x110, v240
	v_lshlrev_b32_e32 v40, 2, v116
	v_add_u32_e32 v43, 0, v35
	v_cndmask_b32_e64 v201, 0, 1.0, vcc
	v_cmp_eq_u32_e32 vcc, 12, v174
	v_add3_u32 v208, s74, v28, v47
	v_or_b32_e32 v28, v48, v114
	v_add_u32_e32 v214, v26, v31
	v_add_u32_e32 v216, v26, v37
	v_bitop3_b32 v26, v30, v29, 40 bitop3:0x6c
	v_add3_u32 v181, s15, v39, v40
	v_lshlrev_b32_e32 v39, 2, v222
	v_cndmask_b32_e64 v202, 0, 1.0, vcc
	v_cmp_eq_u32_e32 vcc, 13, v174
	v_mul_u32_u24_e32 v48, 0x110, v28
	v_bitop3_b32 v28, v27, v36, 56 bitop3:0x6c
	v_lshl_add_u32 v222, v26, 1, v43
	v_or_b32_e32 v26, 16, v30
	v_cndmask_b32_e64 v203, 0, 1.0, vcc
	v_cmp_eq_u32_e32 vcc, 14, v174
	v_lshl_add_u32 v215, v28, 1, v23
	v_mul_u32_u24_e32 v28, 0x48, v26
	s_add_i32 s44, 0, 0x1f500
	v_lshl_or_b32 v46, v25, 1, 1
	v_cndmask_b32_e64 v204, 0, 1.0, vcc
	v_cmp_eq_u32_e32 vcc, 15, v174
	v_lshl_add_u32 v28, v28, 1, 0
	v_bitop3_b32 v29, v26, v29, 56 bitop3:0x6c
	v_bitop3_b32 v26, v26, v36, 56 bitop3:0x6c
	v_lshl_or_b32 v25, v25, 5, v114
	s_cmp_lg_u32 0, -1
	v_cndmask_b32_e64 v205, 0, 1.0, vcc
	v_lshl_add_u32 v224, v29, 1, v28
	v_lshl_add_u32 v226, v26, 1, v28
	v_or_b32_e32 v28, 1, v25
	v_cmp_eq_u32_e32 vcc, v25, v27
	v_add_u32_e32 v41, s15, v39
	s_cselect_b64 s[76:77], -1, 0
	v_mov_b32_e32 v44, s15
	s_add_i32 s15, 0, 0x1fe80
	v_bitop3_b32 v29, v30, v36, 40 bitop3:0x6c
	v_cmp_lt_u32_e64 s[18:19], v28, v27
	v_cndmask_b32_e64 v122, 0, 1.0, vcc
	v_cmp_eq_u32_e32 vcc, v28, v27
	v_or_b32_e32 v28, 3, v25
	v_add_u32_e32 v33, s14, v32
	v_mad_u32_u24 v44, v27, s16, v44
	v_add_u32_e32 v206, v189, v47
	v_add3_u32 v47, s15, v120, v47
	v_add3_u32 v217, s14, v37, v35
	v_lshl_add_u32 v225, v29, 1, v43
	v_cmp_lt_u32_e64 s[14:15], v25, v27
	v_cmp_gt_u32_e64 s[16:17], v25, v27
	v_lshlrev_b32_e32 v29, 2, v25
	v_lshlrev_b32_e32 v26, 1, v25
	v_cndmask_b32_e64 v123, 0, 1.0, vcc
	v_or_b32_e32 v25, 2, v25
	v_cmp_eq_u32_e32 vcc, v28, v27
	s_load_dwordx2 s[78:79], s[0:1], 0xb8
	s_load_dwordx4 s[60:63], s[0:1], 0x18
	s_load_dwordx2 s[80:81], s[0:1], 0x30
	s_load_dwordx4 s[64:67], s[0:1], 0x40
	s_load_dwordx2 s[82:83], s[0:1], 0x50
	s_load_dwordx2 s[84:85], s[0:1], 0xf0
	v_cmp_lt_u32_e64 s[20:21], v25, v27
	v_cmp_gt_u32_e64 s[22:23], v25, v27
	v_cndmask_b32_e64 v125, 0, 1.0, vcc
	v_cmp_eq_u32_e32 vcc, v25, v27
	v_lshl_or_b32 v25, v46, 4, v114
	s_load_dwordx8 s[52:59], s[0:1], 0xd0
	v_mov_b32_e32 v119, 0
	v_lshlrev_b32_e32 v30, 2, v25
	v_or_b32_e32 v118, 0x1800, v40
	v_add_u32_e32 v183, s44, v40
	v_lshl_add_u32 v228, v27, 2, s44
	v_add_u32_e32 v229, v44, v29
	v_cmp_lt_u32_e64 s[24:25], v28, v27
	v_cmp_gt_u32_e64 s[26:27], v28, v27
	v_cndmask_b32_e64 v124, 0, 1.0, vcc
	v_add_u32_e32 v234, s44, v29
	v_or_b32_e32 v29, 1, v25
	v_lshlrev_b32_e32 v28, 1, v25
	v_cmp_eq_u32_e32 vcc, v25, v27
	v_add_u32_e32 v243, s44, v30
	s_waitcnt lgkmcnt(0)
; __device__ __forceinline__ float bflo(unsigned v) { return __uint_as_float(v << 16); }
; __device__ __forceinline__ float bfhi(unsigned v) { return __uint_as_float(v & 0xffff0000u); }
; __device__ void rwkv_prep_item(const Params& p, char* lds_, int item, PrepRaw& raw, int next_item) {
;     ...
;     auto ldshift = [&](int col, float (&o)[8], const u32x4 cur) {
;       u32x4 prv; prv.x = prv.y = prv.z = prv.w = 0u;
;       if (hasprev) prv = *(const u32x4*)(prow - PBW + col);
;       const f32x4 m0 = *(const f32x4*)(p.shift_mu + col), m1 = *(const f32x4*)(p.shift_mu + col + 4);
;       const unsigned cw[4] = {cur.x, cur.y, cur.z, cur.w}, pw[4] = {prv.x, prv.y, prv.z, prv.w};
; #pragma unroll
;       for (int q = 0; q < 4; ++q) {
;         const float c0 = bflo(cw[q]), c1 = bfhi(cw[q]), p0 = bflo(pw[q]), p1 = bfhi(pw[q]);
;         const float mu0 = (q < 2) ? m0[2 * q] : m1[2 * q - 4], mu1 = (q < 2) ? m0[2 * q + 1] : m1[2 * q - 3];
;         o[2 * q] = c0 + (p0 - c0) * mu0;
;         o[2 * q + 1] = c1 + (p1 - c1) * mu1;
;       }
;     };
;     ldshift(hd * 64 + cg8, rr, raw.cur[0]);
;     ldshift(512 + hd * 64 + cg8, kk_, raw.cur[1]);
;     ldshift(1024 + hd * 64 + cg8, vv, raw.cur[2]);
;     float wd[8], ad[8];
;     ldshift(1536 + cg8, wd, raw.cur[3]);
;     ldshift(1600 + cg8, ad, raw.cur[4]);
	v_lshl_add_u64 v[130:131], s[60:61], 0, v[118:119]
	v_or_b32_e32 v118, 0x1900, v40
	s_load_dwordx4 s[44:47], s[0:1], 0x128
	v_add_u32_e32 v38, s4, v32
	v_add_u32_e32 v187, v23, v31
	v_lshl_add_u32 v221, v115, 3, v23
	v_add_u32_e32 v233, v23, v26
	v_add_u32_e32 v239, v23, v28
	v_cndmask_b32_e64 v126, 0, 1.0, vcc
	v_cmp_eq_u32_e32 vcc, v29, v27
	v_or_b32_e32 v23, 3, v25
	v_lshl_add_u64 v[132:133], s[60:61], 0, v[118:119]
	v_lshlrev_b32_e32 v118, 7, v240
	v_add_u32_e32 v162, v33, v31
	v_add_u32_e32 v34, s10, v31
	v_add_u32_e32 v166, v38, v31
	v_add_u32_e32 v188, v43, v31
	v_add_u32_e32 v235, v44, v30
	v_cndmask_b32_e64 v127, 0, 1.0, vcc
	v_cmp_lt_u32_e64 s[40:41], v23, v27
	v_cmp_gt_u32_e64 s[42:43], v23, v27
	v_cmp_eq_u32_e32 vcc, v23, v27
	v_mov_b32_e32 v23, v119
	v_lshl_add_u64 v[30:31], s[84:85], 0, v[118:119]
	v_lshlrev_b32_e32 v118, 7, v27
	v_cmp_lt_u32_e64 s[28:29], v25, v27
	v_cmp_gt_u32_e64 s[30:31], v25, v27
	v_or_b32_e32 v25, 2, v25
	v_lshl_add_u64 v[134:135], s[52:53], 0, v[22:23]
	v_lshl_add_u64 v[136:137], s[54:55], 0, v[22:23]
	v_lshl_add_u64 v[138:139], v[30:31], 0, v[22:23]
	v_lshl_add_u64 v[22:23], s[56:57], 0, v[118:119]
	v_mov_b32_e32 v121, v119
	v_cmp_lt_u32_e64 s[36:37], v25, v27
	v_cmp_gt_u32_e64 s[38:39], v25, v27
	v_cndmask_b32_e64 v129, 0, 1.0, vcc
	v_cmp_eq_u32_e32 vcc, v25, v27
	v_lshl_add_u64 v[22:23], v[22:23], 0, v[120:121]
	v_mov_b32_e32 v25, v119
	v_cmp_lt_u32_e64 s[34:35], v29, v27
	v_lshl_add_u64 v[140:141], v[22:23], 0, v[24:25]
	s_waitcnt lgkmcnt(0)
	v_lshl_add_u64 v[22:23], s[44:45], 0, v[118:119]
	v_mov_b32_e32 v27, v119
	v_mov_b32_e32 v29, v119
	v_add_u32_e32 v163, v34, v35
	v_add3_u32 v164, s10, v35, v37
	v_add3_u32 v165, s10, v37, v35
	v_add3_u32 v169, s5, v37, v35
	v_mul_u32_u24_e32 v42, 0x880, v158
	v_add_u32_e32 v45, s10, v32
	s_movk_i32 s10, 0x80
	v_mul_u32_u24_e32 v51, 0x44, v115
	s_movk_i32 s12, 0x100
	v_mul_u32_u24_e32 v53, 0x84, v115
	v_lshlrev_b32_e32 v35, 5, v46
	v_lshl_add_u64 v[142:143], v[22:23], 0, v[26:27]
	v_lshl_add_u64 v[24:25], s[58:59], 0, v[118:119]
	v_lshl_add_u64 v[30:31], s[46:47], 0, v[118:119]
	v_lshl_add_u64 v[148:149], v[22:23], 0, v[28:29]
	v_add_u32_e32 v22, -1, v158
	v_bfe_u32 v121, v223, 6, 3
	s_mov_b32 s75, 0
	v_lshl_add_u32 v182, v223, 2, s74
	v_cmp_gt_u32_e64 s[4:5], 64, v223
	v_cmp_lt_u32_e64 s[6:7], 63, v223
	v_cmp_eq_u32_e64 s[8:9], 63, v240
	v_add_u32_e32 v186, 0xfd00, v185
	v_cmp_gt_u32_e64 s[10:11], s10, v223
	v_mul_u32_u24_e32 v209, 0x110, v115
	v_cmp_gt_u32_e64 s[12:13], s12, v223
	v_add_u32_e32 v210, v44, v114
	v_add_u32_e32 v227, v34, v32
	v_add_u32_e32 v230, v33, v26
	v_add_u32_e32 v231, v38, v26
	v_add_u32_e32 v232, v45, v26
	v_add_u32_e32 v236, v33, v28
	v_add_u32_e32 v237, v38, v28
	v_add_u32_e32 v238, v45, v28
	v_cndmask_b32_e64 v128, 0, 1.0, vcc
	v_lshl_add_u64 v[144:145], v[24:25], 0, v[26:27]
	v_lshl_add_u64 v[146:147], v[30:31], 0, v[26:27]
	v_lshl_add_u64 v[150:151], v[24:25], 0, v[28:29]
	v_lshl_add_u64 v[152:153], v[30:31], 0, v[28:29]
	v_cmp_lt_u32_e64 s[44:45], 6, v22
	v_and_b32_e32 v244, 8, v158
	v_cmp_ne_u32_e64 s[46:47], 0, v121
	v_add_u32_e32 v245, s74, v39
	s_movk_i32 s53, 0xd00
	s_mov_b32 s52, 0xbf1b4598
	v_add_u32_e32 v246, v49, v50
	v_add_u32_e32 v247, v208, v51
	v_add_u32_e32 v248, v49, v48
	v_add_u32_e32 v249, v47, v52
	v_add_u32_e32 v250, v47, v53
	v_add_u32_e32 v251, v221, v35
	v_add_u32_e32 v252, v41, v42
	s_mov_b32 s54, s2
	global_load_dwordx4 v[200:203], v[132:133], off
	s_and_b32 s94, s2, 0x1c0
	v_add_lshl_u32 v196, s94, v240, 7
	v_mov_b32_e32 v197, 0
	v_mov_b64_e32 v[158:159], v[196:197]
	v_lshl_add_u64 v[196:197], v[136:137], 0, v[196:197]
	global_load_dwordx4 v[196:199], v[196:197], off
	v_lshl_add_u64 v[158:159], v[134:135], 0, v[158:159]
	global_load_dwordx4 v[158:161], v[158:159], off
	s_and_b32 s94, s2, 0x1c0
	s_lshl_b32 s94, s94, 2
	v_mov_b32_e32 v25, s94
	s_add_i32 s94, s2, s50
	s_and_b32 s94, s94, 0x1c0
	s_lshl_b32 s94, s94, 2
	v_mov_b32_e32 v26, s94
	v_lshrrev_b32_e32 v22, 4, v223
	v_and_b32_e32 v23, 15, v223
	v_cmp_lt_u32_e32 vcc, 4, v22
	s_nop 1
	v_cndmask_b32_e32 v25, v25, v26, vcc
	v_cndmask_b32_e64 v24, 0, 5, vcc
	v_sub_u32_e32 v22, v22, v24
	v_lshl_add_u32 v24, v22, 11, v25
	v_lshlrev_b32_e32 v26, 8, v22
	v_add_u32_e32 v26, 0x1500, v26
	v_cmp_gt_u32_e32 vcc, 3, v22
	s_nop 1
	v_cndmask_b32_e32 v24, v26, v24, vcc
	v_lshl_add_u32 v24, v23, 4, v24
	v_lshlrev_b32_e32 v23, 4, v223
	v_add_u32_e32 v23, 0x23a00, v23
	v_cmp_gt_u32_e32 vcc, 0xa0, v223
	s_and_saveexec_b64 s[94:95], vcc
	global_load_dwordx4 v[26:29], v24, s[60:61]
	s_waitcnt vmcnt(0)
	ds_write_b128 v23, v[26:29]
	s_waitcnt lgkmcnt(0)
	s_or_b64 exec, exec, s[94:95]
	s_branch .LBB0_277

; __device__ __forceinline__ float bflo(unsigned v) { return __uint_as_float(v << 16); }
; __device__ __forceinline__ float bfhi(unsigned v) { return __uint_as_float(v & 0xffff0000u); }
; __device__ void rwkv_prep_item(const Params& p, char* lds_, int item, PrepRaw& raw, int next_item) {
;     ...
;     auto ldshift = [&](int col, float (&o)[8], const u32x4 cur) {
;       u32x4 prv; prv.x = prv.y = prv.z = prv.w = 0u;
;       if (hasprev) prv = *(const u32x4*)(prow - PBW + col);
;       const f32x4 m0 = *(const f32x4*)(p.shift_mu + col), m1 = *(const f32x4*)(p.shift_mu + col + 4);
;       const unsigned cw[4] = {cur.x, cur.y, cur.z, cur.w}, pw[4] = {prv.x, prv.y, prv.z, prv.w};
; #pragma unroll
;       for (int q = 0; q < 4; ++q) {
;         const float c0 = bflo(cw[q]), c1 = bfhi(cw[q]), p0 = bflo(pw[q]), p1 = bfhi(pw[q]);
;         const float mu0 = (q < 2) ? m0[2 * q] : m1[2 * q - 4], mu1 = (q < 2) ? m0[2 * q + 1] : m1[2 * q - 3];
;         o[2 * q] = c0 + (p0 - c0) * mu0;
;         o[2 * q + 1] = c1 + (p1 - c1) * mu1;
;       }
;     };
;     ldshift(hd * 64 + cg8, rr, raw.cur[0]);
.LBB0_277:
	s_and_b32 s55, s54, 0x1c0
	s_and_b32 s94, s2, 0x1c0
	s_cmp_lg_u32 s55, s94
	s_cselect_b32 s94, 0x500, 0
	v_and_b32_e32 v220, 7, v223
	v_lshl_add_u32 v220, v220, 5, s94
	v_add_u32_e32 v220, 0x23a00, v220
	v_or_b32_e32 v23, s55, v116
	v_lshlrev_b32_e32 v22, 2, v23
	global_load_dwordx4 v[66:69], v22, s[64:65]
	s_lshl_b32 s57, s54, 6
	s_ashr_i32 s56, s54, 9
	s_and_b32 s57, s57, 0xfc0
	v_add_u32_e32 v118, s57, v240
	s_ashr_i32 s57, s56, 31
	s_lshl_b64 s[56:57], s[56:57], 12
	v_lshl_add_u64 v[24:25], s[56:57], 0, v[118:119]
	v_mov_b64_e32 v[26:27], s[78:79]
	v_mad_u64_u32 v[156:157], s[56:57], v24, s53, v[26:27]
	v_mad_i32_i24 v157, v25, s53, v157
	v_cmp_ne_u32_e32 vcc, 0, v118
	v_lshlrev_b32_e32 v118, 1, v23
	v_mov_b32_e32 v78, 0
	v_mov_b32_e32 v79, 0
	v_mov_b32_e32 v80, 0
	v_mov_b32_e32 v81, 0
	s_barrier
	s_and_saveexec_b64 s[56:57], vcc
	s_cbranch_execz .LBB0_279
	v_lshl_add_u64 v[24:25], v[156:157], 0, v[118:119]
	global_load_dwordx4 v[78:81], v[24:25], off offset:-3328
.LBB0_279:
	s_or_b64 exec, exec, s[56:57]
	ds_read_b128 v[82:85], v220 offset:16
	ds_read_b128 v[86:89], v220
	s_and_saveexec_b64 s[56:57], vcc
	s_xor_b64 s[56:57], exec, s[56:57]
	s_cbranch_execz .LBB0_281
	v_lshl_add_u64 v[24:25], v[156:157], 0, v[118:119]
	global_load_dwordx4 v[90:93], v[24:25], off offset:-2304

; __device__ void rwkv_prep_item(const Params& p, char* lds_, int item, PrepRaw& raw, int next_item) {
;     ...
;     };
;     ldshift(hd * 64 + cg8, rr, raw.cur[0]);
;     ldshift(512 + hd * 64 + cg8, kk_, raw.cur[1]);
.LBB0_283:
	s_or_b64 exec, exec, s[56:57]
	ds_read_b128 v[94:97], v220 offset:272
	ds_read_b128 v[98:101], v220 offset:256
	s_and_saveexec_b64 s[56:57], vcc
	s_xor_b64 s[56:57], exec, s[56:57]
	s_cbranch_execz .LBB0_285
	v_lshl_add_u64 v[22:23], v[156:157], 0, v[118:119]
	global_load_dwordx4 v[22:25], v[22:23], off offset:-1280

; __device__ __forceinline__ unsigned pk2(float lo, float hi) { f32x2_t v = {lo, hi}; bf16x2_t b = __builtin_convertvector(v, bf16x2_t); return __builtin_bit_cast(unsigned, b); }
; __device__ __forceinline__ float bflo(unsigned v) { return __uint_as_float(v << 16); }
; __device__ __forceinline__ float bfhi(unsigned v) { return __uint_as_float(v & 0xffff0000u); }
; __device__ __forceinline__ float fexp(float x) { return __builtin_amdgcn_exp2f(x * 1.44269504088896f); }
; __device__ void rwkv_prep_item(const Params& p, char* lds_, int item, PrepRaw& raw, int next_item) {
;     ...
;     auto ldshift = [&](int col, float (&o)[8], const u32x4 cur) {
;       u32x4 prv; prv.x = prv.y = prv.z = prv.w = 0u;
;       if (hasprev) prv = *(const u32x4*)(prow - PBW + col);
;       const f32x4 m0 = *(const f32x4*)(p.shift_mu + col), m1 = *(const f32x4*)(p.shift_mu + col + 4);
;       const unsigned cw[4] = {cur.x, cur.y, cur.z, cur.w}, pw[4] = {prv.x, prv.y, prv.z, prv.w};
; #pragma unroll
;       for (int q = 0; q < 4; ++q) {
;         const float c0 = bflo(cw[q]), c1 = bfhi(cw[q]), p0 = bflo(pw[q]), p1 = bfhi(pw[q]);
;         const float mu0 = (q < 2) ? m0[2 * q] : m1[2 * q - 4], mu1 = (q < 2) ? m0[2 * q + 1] : m1[2 * q - 3];
;         o[2 * q] = c0 + (p0 - c0) * mu0;
;         o[2 * q + 1] = c1 + (p1 - c1) * mu1;
;       }
;     };
;     ldshift(hd * 64 + cg8, rr, raw.cur[0]);
;     ldshift(512 + hd * 64 + cg8, kk_, raw.cur[1]);
;     ldshift(1024 + hd * 64 + cg8, vv, raw.cur[2]);
;     float wd[8], ad[8];
;     ldshift(1536 + cg8, wd, raw.cur[3]);
;     ldshift(1600 + cg8, ad, raw.cur[4]);
;     u32x4 w;
;     float th[8];
; #pragma unroll
;     for (int e = 0; e < 8; ++e) th[e] = 1.f - 2.f * __builtin_amdgcn_rcpf(1.f + fexp(2.f * wd[e]));
;     w.x = pk2(th[0], th[1]); w.y = pk2(th[2], th[3]); w.z = pk2(th[4], th[5]); w.w = pk2(th[6], th[7]);
.LBB0_287:
	s_or_b64 exec, exec, s[56:57]
	ds_read_b128 v[26:29], v220 offset:528
	s_nop 0
	ds_read_b128 v[30:33], v220 offset:512
	v_mov_b32_e32 v74, 0
	v_lshlrev_b32_e32 v154, 1, v116
	v_mov_b32_e32 v102, 0
	v_mov_b32_e32 v103, 0
	v_mov_b32_e32 v104, 0
	v_mov_b32_e32 v105, 0
	s_and_saveexec_b64 s[56:57], vcc
	s_cbranch_execz .LBB0_289
	v_mov_b32_e32 v155, v119
	v_lshl_add_u64 v[76:77], v[156:157], 0, v[154:155]
	global_load_dwordx4 v[102:105], v[76:77], off offset:-256
.LBB0_289:
	s_or_b64 exec, exec, s[56:57]
	ds_read_b128 v[106:109], v220 offset:784
	ds_read_b128 v[110:113], v220 offset:768
	ds_read_b128 v[192:195], v220 offset:1040
	v_mov_b32_e32 v75, 0
	v_mov_b32_e32 v76, 0
	v_mov_b32_e32 v77, 0
	s_and_saveexec_b64 s[56:57], vcc
	s_cbranch_execz .LBB0_291
	v_mov_b32_e32 v155, v119
	v_lshl_add_u64 v[74:75], v[156:157], 0, v[154:155]
	global_load_dwordx4 v[74:77], v[74:75], off offset:-128
.LBB0_291:
	s_or_b64 exec, exec, s[56:57]
	s_waitcnt vmcnt(6)
	v_lshlrev_b32_e32 v118, 16, v10
	v_and_b32_e32 v155, 0xffff0000, v10
	s_waitcnt vmcnt(0) lgkmcnt(0)
	v_lshlrev_b32_e32 v156, 16, v102
	v_and_b32_e32 v102, 0xffff0000, v102
	v_sub_f32_e32 v156, v156, v118
	v_sub_f32_e32 v102, v102, v155
	s_waitcnt vmcnt(0)
	v_fmac_f32_e32 v118, v110, v156
	v_fmac_f32_e32 v155, v111, v102
	v_lshlrev_b32_e32 v110, 16, v11
	v_lshlrev_b32_e32 v102, 16, v103
	v_and_b32_e32 v111, 0xffff0000, v11
	v_and_b32_e32 v103, 0xffff0000, v103
	v_sub_f32_e32 v102, v102, v110
	v_fmac_f32_e32 v110, v112, v102
	v_sub_f32_e32 v102, v103, v111
	v_fmac_f32_e32 v111, v113, v102
	v_lshlrev_b32_e32 v112, 16, v12
	v_lshlrev_b32_e32 v102, 16, v104
	v_and_b32_e32 v113, 0xffff0000, v12
	v_and_b32_e32 v103, 0xffff0000, v104
	v_sub_f32_e32 v102, v102, v112
	v_fmac_f32_e32 v112, v106, v102
	v_sub_f32_e32 v102, v103, v113
	v_fmac_f32_e32 v113, v107, v102
	v_and_b32_e32 v102, 0xffff0000, v105
	v_and_b32_e32 v156, 0xffff0000, v13
	v_sub_f32_e32 v102, v102, v156
	v_lshlrev_b32_e32 v103, 16, v105
	v_lshlrev_b32_e32 v157, 16, v13
	v_fmac_f32_e32 v156, v109, v102
	v_and_b32_e32 v104, 0xffff0000, v2
	v_lshlrev_b32_e32 v102, 16, v90
	v_and_b32_e32 v90, 0xffff0000, v90
	v_sub_f32_e32 v103, v103, v157
	v_lshlrev_b32_e32 v105, 16, v2
	v_sub_f32_e32 v90, v90, v104
	v_fmac_f32_e32 v157, v108, v103
	v_sub_f32_e32 v102, v102, v105
	v_fmac_f32_e32 v104, v99, v90
	v_lshlrev_b32_e32 v103, 16, v3
	v_lshlrev_b32_e32 v90, 16, v91
	v_fmac_f32_e32 v105, v98, v102
	v_and_b32_e32 v102, 0xffff0000, v3
	v_and_b32_e32 v91, 0xffff0000, v91
	v_sub_f32_e32 v90, v90, v103
	v_fmac_f32_e32 v103, v100, v90
	v_sub_f32_e32 v90, v91, v102
	v_fmac_f32_e32 v102, v101, v90
	v_lshlrev_b32_e32 v99, 16, v4
	v_lshlrev_b32_e32 v90, 16, v92
	v_and_b32_e32 v98, 0xffff0000, v4
	v_and_b32_e32 v91, 0xffff0000, v92
	v_sub_f32_e32 v90, v90, v99
	v_fmac_f32_e32 v99, v94, v90
	v_sub_f32_e32 v90, v91, v98
	v_fmac_f32_e32 v98, v95, v90
	v_and_b32_e32 v90, 0xffff0000, v93
	v_and_b32_e32 v92, 0xffff0000, v5
	v_lshlrev_b32_e32 v91, 16, v93
	v_lshlrev_b32_e32 v93, 16, v5
	v_sub_f32_e32 v90, v90, v92
	v_sub_f32_e32 v91, v91, v93
	v_fmac_f32_e32 v92, v97, v90
	v_and_b32_e32 v90, 0xffff0000, v6
	v_lshlrev_b32_e32 v94, 16, v78
	v_and_b32_e32 v78, 0xffff0000, v78
	v_fmac_f32_e32 v93, v96, v91
	v_lshlrev_b32_e32 v91, 16, v6
	v_sub_f32_e32 v78, v78, v90
	v_sub_f32_e32 v94, v94, v91
	v_fmac_f32_e32 v90, v87, v78
	v_lshlrev_b32_e32 v87, 16, v7
	v_lshlrev_b32_e32 v78, 16, v79
	v_fmac_f32_e32 v91, v86, v94
	v_and_b32_e32 v86, 0xffff0000, v7
	v_and_b32_e32 v79, 0xffff0000, v79
	v_sub_f32_e32 v78, v78, v87
	v_fmac_f32_e32 v87, v88, v78
	v_sub_f32_e32 v78, v79, v86
	v_fmac_f32_e32 v86, v89, v78
	v_lshlrev_b32_e32 v89, 16, v8
	v_lshlrev_b32_e32 v78, 16, v80
	v_and_b32_e32 v88, 0xffff0000, v8
	v_and_b32_e32 v79, 0xffff0000, v80
	v_sub_f32_e32 v78, v78, v89
	v_fmac_f32_e32 v89, v78, v82
	v_sub_f32_e32 v78, v79, v88
	v_fmac_f32_e32 v88, v78, v83
	v_and_b32_e32 v78, 0xffff0000, v81
	v_lshlrev_b32_e32 v79, 16, v81
	v_and_b32_e32 v82, 0xffff0000, v9
	v_lshlrev_b32_e32 v83, 16, v9
	v_sub_f32_e32 v79, v79, v83
	v_sub_f32_e32 v78, v78, v82
	v_fmac_f32_e32 v83, v79, v84
	v_fmac_f32_e32 v82, v78, v85
	v_add_f32_e32 v84, v118, v118
	v_add_f32_e32 v85, v155, v155
	v_add_f32_e32 v100, v110, v110
	v_add_f32_e32 v101, v111, v111
	v_add_f32_e32 v106, v112, v112
	v_add_f32_e32 v107, v113, v113
	v_add_f32_e32 v108, v157, v157
	v_add_f32_e32 v109, v156, v156
	v_mul_f32_e32 v84, 0x3fb8aa3b, v84
	v_mul_f32_e32 v85, 0x3fb8aa3b, v85
	v_mul_f32_e32 v100, 0x3fb8aa3b, v100
	v_mul_f32_e32 v101, 0x3fb8aa3b, v101
	v_mul_f32_e32 v106, 0x3fb8aa3b, v106
	v_mul_f32_e32 v107, 0x3fb8aa3b, v107
	v_mul_f32_e32 v108, 0x3fb8aa3b, v108
	v_mul_f32_e32 v109, 0x3fb8aa3b, v109
	v_exp_f32_e32 v84, v84
	v_exp_f32_e32 v85, v85
	v_exp_f32_e32 v100, v100
	v_exp_f32_e32 v101, v101
	v_exp_f32_e32 v106, v106
	v_exp_f32_e32 v107, v107
	v_exp_f32_e32 v108, v108
	v_exp_f32_e32 v109, v109
	v_lshlrev_b32_e32 v110, 16, v14
	v_and_b32_e32 v111, 0xffff0000, v14
	v_lshlrev_b32_e32 v112, 16, v74
	v_and_b32_e32 v113, 0xffff0000, v74
	v_pk_add_f32 v[112:113], v[112:113], v[110:111] neg_lo:[0,1] neg_hi:[0,1]
	v_add_f32_e32 v84, 1.0, v84
	v_add_f32_e32 v85, 1.0, v85
	v_add_f32_e32 v100, 1.0, v100
	v_add_f32_e32 v101, 1.0, v101
	v_add_f32_e32 v106, 1.0, v106
	v_add_f32_e32 v107, 1.0, v107
	v_add_f32_e32 v108, 1.0, v108
	v_add_f32_e32 v109, 1.0, v109
	v_lshlrev_b32_e32 v74, 16, v75
	v_and_b32_e32 v75, 0xffff0000, v75
	v_rcp_f32_e32 v84, v84
	v_rcp_f32_e32 v85, v85
	v_rcp_f32_e32 v100, v100
	v_rcp_f32_e32 v101, v101
	v_rcp_f32_e32 v106, v106
	v_rcp_f32_e32 v107, v107
	v_rcp_f32_e32 v108, v108
	v_rcp_f32_e32 v109, v109
	v_pk_fma_f32 v[84:85], v[84:85], 2.0, 1.0 op_sel_hi:[1,0,0] neg_lo:[1,0,0] neg_hi:[1,0,0]
	v_pk_fma_f32 v[100:101], v[100:101], 2.0, 1.0 op_sel_hi:[1,0,0] neg_lo:[1,0,0] neg_hi:[1,0,0]
	v_pk_fma_f32 v[106:107], v[106:107], 2.0, 1.0 op_sel_hi:[1,0,0] neg_lo:[1,0,0] neg_hi:[1,0,0]
	v_pk_fma_f32 v[108:109], v[108:109], 2.0, 1.0 op_sel_hi:[1,0,0] neg_lo:[1,0,0] neg_hi:[1,0,0]
	v_add_lshl_u32 v118, s55, v240, 7
	v_mul_f32_e32 v67, v67, v104
	v_mul_f32_e32 v66, v66, v105
	v_mul_f32_e32 v68, v68, v103
	v_mul_f32_e32 v69, v69, v102
	s_add_i32 s90, s54, s50
	s_waitcnt vmcnt(0)
; __device__ __forceinline__ unsigned pk2(float lo, float hi) { f32x2_t v = {lo, hi}; bf16x2_t b = __builtin_convertvector(v, bf16x2_t); return __builtin_bit_cast(unsigned, b); }
; __device__ void rwkv_prep_item(const Params& p, char* lds_, int item, PrepRaw& raw, int next_item) {
;     ...
;     w.x = pk2(th[0], th[1]); w.y = pk2(th[2], th[3]); w.z = pk2(th[4], th[5]); w.w = pk2(th[6], th[7]);
;     *(u32x4*)(TW + t * LD + cg8) = w;
;     w.x = pk2(ad[0], ad[1]); w.y = pk2(ad[2], ad[3]); w.z = pk2(ad[4], ad[5]); w.w = pk2(ad[6], ad[7]);
;     *(u32x4*)(AD + t * LD + cg8) = w;
;     *(u32x4*)(DUs + t * LD + cg8) = *(const u32x4*)(p.DUt + (size_t)(hd * 64 + t) * 64 + cg8);
;     *(u32x4*)(IUs + t * LD + cg8) = *(const u32x4*)(p.IUt + (size_t)(hd * 64 + t) * 64 + cg8);
;   }
;   __syncthreads();
;   const int it = wave >> 1, jt0 = (wave & 1) * 2, mr = lane & 15, mg = lane >> 4;
;   const int mi = it * 16 + mr;
;   {
;     f32x4 a1[2], a2[2]; zero2(a1); zero2(a2);
;     mm_nt(TW, DUs, a1, wave, lane);
;     mm_nt(AD, IUs, a2, wave, lane);
; #pragma unroll
;     for (int jj = 0; jj < 2; ++jj) {
;       *(f32x4*)(Zw + mi * 68 + (jt0 + jj) * 16 + 4 * mg) = a1[jj];
;       *(f32x4*)(Za + mi * 68 + (jt0 + jj) * 16 + 4 * mg) = a2[jj];
;     }
;   }
;   __syncthreads();
	v_pk_fma_f32 v[94:95], v[200:201], v[112:113], v[110:111]
	v_lshlrev_b32_e32 v110, 16, v15
	v_and_b32_e32 v111, 0xffff0000, v15
	v_pk_add_f32 v[74:75], v[74:75], v[110:111] neg_lo:[0,1] neg_hi:[0,1]
	s_nop 0
	v_pk_fma_f32 v[96:97], v[202:203], v[74:75], v[110:111]
	v_lshlrev_b32_e32 v74, 16, v16
	v_and_b32_e32 v75, 0xffff0000, v16
	v_lshlrev_b32_e32 v110, 16, v76
	v_and_b32_e32 v111, 0xffff0000, v76
	v_pk_add_f32 v[110:111], v[110:111], v[74:75] neg_lo:[0,1] neg_hi:[0,1]
	v_lshlrev_b32_e32 v76, 16, v17
	v_pk_fma_f32 v[78:79], v[192:193], v[110:111], v[74:75]
	v_lshlrev_b32_e32 v74, 16, v77
	v_and_b32_e32 v75, 0xffff0000, v77
	v_and_b32_e32 v77, 0xffff0000, v17
	v_pk_add_f32 v[74:75], v[74:75], v[76:77] neg_lo:[0,1] neg_hi:[0,1]
	s_nop 0
	v_pk_fma_f32 v[80:81], v[194:195], v[74:75], v[76:77]
	v_cvt_pk_bf16_f32 v74, v84, v85
	v_cvt_pk_bf16_f32 v75, v100, v101
	v_cvt_pk_bf16_f32 v76, v106, v107
	v_cvt_pk_bf16_f32 v77, v108, v109
	ds_write_b128 v117, v[74:77]
	v_cvt_pk_bf16_f32 v74, v94, v95
	v_cvt_pk_bf16_f32 v75, v96, v97
	v_cvt_pk_bf16_f32 v76, v78, v79
	v_cvt_pk_bf16_f32 v77, v80, v81
	ds_write_b128 v117, v[74:77] offset:9216
	v_mul_f32_e32 v85, v67, v67
	v_fmac_f32_e32 v85, v66, v66
	v_fmac_f32_e32 v85, v68, v68
	v_fmac_f32_e32 v85, v69, v69
	ds_write_b128 v117, v[158:161] offset:18432
	ds_write_b128 v117, v[196:199] offset:27648
	s_and_b32 s94, s90, 0x1c0
	v_add_lshl_u32 v196, s94, v240, 7
	v_mov_b32_e32 v197, 0
	v_mov_b64_e32 v[158:159], v[196:197]
	v_lshl_add_u64 v[196:197], v[136:137], 0, v[196:197]
	global_load_dwordx4 v[196:199], v[196:197], off
	v_lshl_add_u64 v[158:159], v[134:135], 0, v[158:159]
	global_load_dwordx4 v[158:161], v[158:159], off
	v_or_b32_e32 v58, s55, v116
	v_lshlrev_b32_e32 v58, 2, v58
	global_load_dwordx4 v[34:37], v58, s[62:63] offset:16
	global_load_dwordx4 v[38:41], v58, s[62:63]
	global_load_dwordx4 v[54:57], v58, s[80:81] offset:16
	global_load_dwordx4 v[70:73], v58, s[80:81]
	global_load_dwordx4 v[46:49], v58, s[64:65] offset:16
	global_load_dwordx4 v[50:53], v58, s[66:67] offset:16
	global_load_dwordx4 v[62:65], v58, s[66:67]
	global_load_dwordx4 v[42:45], v58, s[82:83] offset:16
	global_load_dwordx4 v[58:61], v58, s[82:83]
	s_waitcnt lgkmcnt(0)
	s_barrier
	ds_read_b128 v[74:77], v162
	ds_read_b128 v[78:81], v163
	ds_read_b128 v[94:97], v163 offset:2304
	s_waitcnt lgkmcnt(1)
	v_mfma_f32_16x16x32_bf16 v[78:81], v[78:81], v[74:77], 0
	s_waitcnt lgkmcnt(0)
	v_mfma_f32_16x16x32_bf16 v[74:77], v[94:97], v[74:77], 0
	ds_read_b128 v[94:97], v162 offset:64
	ds_read_b128 v[106:109], v164
	s_waitcnt lgkmcnt(0)
	v_mfma_f32_16x16x32_bf16 v[78:81], v[106:109], v[94:97], v[78:81]
	ds_read_b128 v[106:109], v165 offset:2304
	s_waitcnt lgkmcnt(0)
	v_mfma_f32_16x16x32_bf16 v[74:77], v[106:109], v[94:97], v[74:77]
	ds_read_b128 v[94:97], v166
	ds_read_b128 v[106:109], v167
	ds_read_b128 v[110:113], v167 offset:2304
	s_waitcnt lgkmcnt(1)
	v_mfma_f32_16x16x32_bf16 v[106:109], v[106:109], v[94:97], 0
	s_waitcnt lgkmcnt(0)
	v_mfma_f32_16x16x32_bf16 v[94:97], v[110:113], v[94:97], 0
	ds_read_b128 v[110:113], v166 offset:64
	ds_read_b128 v[192:195], v168
	s_waitcnt lgkmcnt(0)
	v_mfma_f32_16x16x32_bf16 v[106:109], v[192:195], v[110:113], v[106:109]
	ds_read_b128 v[192:195], v169 offset:2304
	s_waitcnt lgkmcnt(0)
	v_mfma_f32_16x16x32_bf16 v[94:97], v[192:195], v[110:113], v[94:97]
	ds_write_b128 v170, v[78:81]
	s_nop 3
	ds_write_b128 v171, v[106:109]
	ds_write_b128 v170, v[74:77] offset:64
	s_nop 0
	ds_write_b128 v171, v[94:97] offset:64
	s_waitcnt lgkmcnt(0)
	s_barrier
; __device__ __forceinline__ float fsigmoid(float x) { return __builtin_amdgcn_rcpf(1.f + fexp(-x)); }
; __device__ void rwkv_prep_item(const Params& p, char* lds_, int item, PrepRaw& raw, int next_item) {
;     ...
;   float av[8], bv[8], k2[8], lw[8];
;   float bon;
;   {
;     float ss = 0.f; bon = 0.f;
;     float kk[8], ai[8];
; #pragma unroll
;     for (int e = 0; e < 8; ++e) {
;       const float zw = Zw[t * 68 + cg8 + e] + pdb[e >> 2][e & 3];
;       const float za = Za[t * 68 + cg8 + e] + pib[e >> 2][e & 3];
;       lw[e] = -0.6065306597126334f * fsigmoid(zw);
;       ai[e] = fsigmoid(za);
;       kk[e] = kk_[e] * pkk[e >> 2][e & 3];
;       k2[e] = kk_[e] * (1.f + (ai[e] - 1.f) * pka[e >> 2][e & 3]);
;       ss += kk[e] * kk[e];
;       bon += rr[e] * k2[e] * prk[e >> 2][e & 3];
;     }
;     ss += __shfl_xor(ss, 1); ss += __shfl_xor(ss, 2); ss += __shfl_xor(ss, 4);
;     bon += __shfl_xor(bon, 1); bon += __shfl_xor(bon, 2); bon += __shfl_xor(bon, 4);
;     const float inv = __builtin_amdgcn_rsqf(fmaxf(ss, 1e-24f));
; #pragma unroll
;     for (int e = 0; e < 8; ++e) { const float kn = kk[e] * inv; av[e] = -kn; bv[e] = kn * ai[e]; }
;   }
;   __builtin_amdgcn_sched_barrier(0);
;   if (next_item < 4096) prep_load(p, next_item, raw);
	ds_read_b128 v[74:77], v172
	ds_read_b128 v[78:81], v173
	s_waitcnt vmcnt(0) lgkmcnt(0)
	v_add_f32_e32 v70, v70, v78
	v_mul_f32_e32 v70, 0xbfb8aa3b, v70
	v_exp_f32_e32 v70, v70
	s_nop 0
	v_add_f32_e32 v70, 1.0, v70
	v_rcp_f32_e32 v70, v70
	s_nop 0
	v_add_f32_e32 v78, -1.0, v70
	v_fma_f32 v62, v62, v78, 1.0
	v_mul_f32_e32 v62, v105, v62
	v_mul_f32_e32 v78, v91, v62
	v_fma_f32 v84, v58, v78, 0
	v_add_f32_e32 v58, v71, v79
	v_mul_f32_e32 v58, 0xbfb8aa3b, v58
	v_exp_f32_e32 v58, v58
	s_nop 0
	v_add_f32_e32 v58, 1.0, v58
	v_rcp_f32_e32 v71, v58
	s_nop 0
	v_add_f32_e32 v58, -1.0, v71
	v_fma_f32 v58, v63, v58, 1.0
	v_mul_f32_e32 v63, v104, v58
	v_mul_f32_e32 v58, v90, v63
	v_fmac_f32_e32 v84, v59, v58
	v_add_f32_e32 v58, v72, v80
	v_mul_f32_e32 v58, 0xbfb8aa3b, v58
	v_exp_f32_e32 v58, v58
	s_nop 0
	v_add_f32_e32 v58, 1.0, v58
	v_rcp_f32_e32 v72, v58
	s_nop 0
	v_add_f32_e32 v58, -1.0, v72
	v_fma_f32 v58, v64, v58, 1.0
	v_mul_f32_e32 v64, v103, v58
	v_mul_f32_e32 v58, v87, v64
	v_fmac_f32_e32 v84, v60, v58
	v_add_f32_e32 v58, v73, v81
	v_mul_f32_e32 v58, 0xbfb8aa3b, v58
	v_exp_f32_e32 v58, v58
	s_nop 0
	v_add_f32_e32 v58, 1.0, v58
	v_rcp_f32_e32 v73, v58
	s_nop 0
	v_add_f32_e32 v58, -1.0, v73
	v_fma_f32 v58, v65, v58, 1.0
	v_mul_f32_e32 v65, v102, v58
	v_mul_f32_e32 v58, v86, v65
	v_fmac_f32_e32 v84, v61, v58
	ds_read_b128 v[58:61], v176
	ds_read_b128 v[78:81], v177
	s_waitcnt lgkmcnt(0)
	v_add_f32_e32 v54, v54, v78
	v_mul_f32_e32 v54, 0xbfb8aa3b, v54
	v_exp_f32_e32 v54, v54
	v_mul_f32_e32 v78, v46, v99
	v_fmac_f32_e32 v85, v78, v78
	v_add_f32_e32 v54, 1.0, v54
	v_rcp_f32_e32 v54, v54
	s_nop 0
	v_add_f32_e32 v46, -1.0, v54
	v_fma_f32 v46, v50, v46, 1.0
	v_mul_f32_e32 v46, v99, v46
	v_mul_f32_e32 v50, v89, v46
	v_fmac_f32_e32 v84, v42, v50
	v_add_f32_e32 v42, v55, v79
	v_mul_f32_e32 v42, 0xbfb8aa3b, v42
	v_exp_f32_e32 v42, v42
	v_mul_f32_e32 v55, v47, v98
	v_fmac_f32_e32 v85, v55, v55
	v_mul_f32_e32 v79, v49, v92
	v_add_f32_e32 v42, 1.0, v42
	v_rcp_f32_e32 v50, v42
	s_nop 0
	v_add_f32_e32 v42, -1.0, v50
	v_fma_f32 v42, v51, v42, 1.0
	v_mul_f32_e32 v47, v98, v42
	v_mul_f32_e32 v42, v88, v47
	v_fmac_f32_e32 v84, v43, v42
	v_add_f32_e32 v42, v56, v80
	v_mul_f32_e32 v42, 0xbfb8aa3b, v42
	v_exp_f32_e32 v42, v42
	v_mul_f32_e32 v56, v48, v93
	v_fmac_f32_e32 v85, v56, v56
	v_fmac_f32_e32 v85, v79, v79
	v_add_f32_e32 v42, 1.0, v42
	v_rcp_f32_e32 v51, v42
	s_nop 0
	v_add_f32_e32 v42, -1.0, v51
	v_fma_f32 v42, v52, v42, 1.0
	v_mul_f32_e32 v52, v93, v42
	v_mul_f32_e32 v42, v83, v52
	v_fmac_f32_e32 v84, v44, v42
	v_add_f32_e32 v42, v57, v81
	v_mul_f32_e32 v42, 0xbfb8aa3b, v42
	v_exp_f32_e32 v42, v42
	s_nop 0
	v_add_f32_e32 v42, 1.0, v42
	v_rcp_f32_e32 v57, v42
	s_nop 0
	v_add_f32_e32 v42, -1.0, v57
	v_fma_f32 v42, v53, v42, 1.0
	v_mul_f32_e32 v53, v92, v42
	v_mul_f32_e32 v42, v82, v53
	v_fmac_f32_e32 v84, v45, v42
	ds_bpermute_b32 v42, v178, v85
	s_waitcnt lgkmcnt(0)
	v_add_f32_e32 v42, v85, v42
	ds_bpermute_b32 v43, v179, v42
	s_waitcnt lgkmcnt(0)
	v_add_f32_e32 v80, v42, v43
	ds_bpermute_b32 v42, v178, v84
	ds_bpermute_b32 v81, v180, v80
	s_waitcnt lgkmcnt(1)
	v_add_f32_e32 v42, v84, v42
	ds_bpermute_b32 v43, v179, v42
	s_waitcnt lgkmcnt(0)
	v_add_f32_e32 v48, v42, v43
	ds_bpermute_b32 v49, v180, v48
	s_cmpk_gt_i32 s90, 0xfff
	s_cselect_b64 s[56:57], -1, 0
	v_mov_b64_e32 v[44:45], v[20:21]
	s_and_b64 vcc, exec, s[56:57]
	v_mov_b64_e32 v[42:43], v[18:19]
	s_cbranch_vccnz .LBB0_293
	s_ashr_i32 s58, s90, 9
	s_lshl_b32 s74, s90, 6
	s_ashr_i32 s59, s58, 31
	s_and_b32 s74, s74, 0xfc0
	s_lshl_b64 s[58:59], s[58:59], 12
	v_add_u32_e32 v118, s74, v240
	v_lshl_add_u64 v[2:3], s[58:59], 0, v[118:119]
	v_mov_b64_e32 v[4:5], s[78:79]
	s_and_b32 s55, s90, 0x1c0
	v_mad_u64_u32 v[10:11], s[58:59], v2, s53, v[4:5]
	v_mad_i32_i24 v11, v3, s53, v11
	s_lshl_b32 s74, s55, 1
	v_lshl_add_u64 v[2:3], v[10:11], 0, s[74:75]
	v_mov_b32_e32 v155, v119
	v_lshl_add_u64 v[12:13], v[2:3], 0, v[154:155]
	v_lshl_add_u64 v[14:15], v[10:11], 0, v[154:155]
	global_load_dwordx4 v[6:9], v[12:13], off
	global_load_dwordx4 v[2:5], v[12:13], off offset:1024
	global_load_dwordx4 v[42:45], v[12:13], off offset:2048
	s_nop 0
	global_load_dwordx4 v[10:13], v[14:15], off offset:3072
	s_nop 0
	global_load_dwordx4 v[14:17], v[14:15], off offset:3200
